# adds: P5 residual/norm epilogue hand-written, x loads four row groups ahead with counted waits
# speedup vs baseline: 1.0031x; 1.0002x over previous
.LBB0_589:
	s_ashr_i32 s19, s50, 31
	s_lshr_b32 s19, s19, 27
	s_add_i32 s19, s50, s19
	s_ashr_i32 s19, s19, 5
	s_mul_hi_i32 s25, s19, 0x6000
	s_mulk_i32 s19, 0x6000
	s_add_u32 s26, s39, s19
	s_addc_u32 s27, s40, s25
	v_lshl_or_b32 v252, s24, 8, v174
	s_add_u32 s24, s41, s19
	s_addc_u32 s25, s42, s25
	v_lshl_add_u32 v253, s50, 8, v172
	v_lshlrev_b32_e32 v179, 12, v253
	v_lshl_add_u32 v179, v252, 2, v179
	v_lshlrev_b32_e32 v253, 2, v253
	v_lshlrev_b32_e32 v248, 2, v252
	v_lshrrev_b32_e32 v252, 1, v179
	global_load_dwordx4 v[180:183], v248, s[26:27]
	global_load_dwordx4 v[184:187], v248, s[26:27] offset:16
	global_load_dwordx4 v[188:191], v248, s[26:27] offset:512
	global_load_dwordx4 v[192:195], v248, s[26:27] offset:528
	global_load_dwordx4 v[212:215], v248, s[8:9]
	global_load_dwordx4 v[216:219], v248, s[8:9] offset:16
	global_load_dwordx4 v[220:223], v248, s[8:9] offset:512
	global_load_dwordx4 v[224:227], v248, s[8:9] offset:528
	global_load_dwordx4 v[196:199], v248, s[78:79]
	global_load_dwordx4 v[200:203], v248, s[78:79] offset:16
	global_load_dwordx4 v[204:207], v248, s[78:79] offset:512
	global_load_dwordx4 v[208:211], v248, s[78:79] offset:528
	global_load_dwordx4 v[228:231], v248, s[24:25]
	global_load_dwordx4 v[232:235], v248, s[24:25] offset:16
	global_load_dwordx4 v[236:239], v248, s[24:25] offset:512
	global_load_dwordx4 v[240:243], v248, s[24:25] offset:528
	global_load_dwordx4 v[144:147], v248, s[10:11]
	global_load_dwordx4 v[148:151], v248, s[10:11] offset:16
	global_load_dwordx4 v[152:155], v248, s[10:11] offset:512
	global_load_dwordx4 v[156:159], v248, s[10:11] offset:528
	s_mov_b32 s18, s52
	s_mov_b32 s19, s53
	global_load_dwordx4 v[160:163], v179, s[18:19] nt
	global_load_dwordx4 v[164:167], v179, s[18:19] offset:16 nt
	global_load_dwordx4 v[168:171], v179, s[18:19] offset:512 nt
	global_load_dwordx4 v[244:247], v179, s[18:19] offset:528 nt
	s_add_u32 s18, s18, 0x10000
	s_addc_u32 s19, s19, 0
	s_waitcnt vmcnt(4)
	v_pk_add_f32 v[182:183], v[182:183], v[214:215]
	v_pk_add_f32 v[180:181], v[180:181], v[212:213]
	v_pk_add_f32 v[230:231], v[230:231], v[146:147]
	v_pk_add_f32 v[228:229], v[228:229], v[144:145]
	v_pk_add_f32 v[230:231], v[230:231], 1.0 op_sel_hi:[1,0]
	v_pk_add_f32 v[228:229], v[228:229], 1.0 op_sel_hi:[1,0]
	v_pk_mul_f32 v[198:199], v[198:199], v[230:231]
	v_pk_mul_f32 v[196:197], v[196:197], v[228:229]
	v_pk_add_f32 v[186:187], v[186:187], v[218:219]
	v_pk_add_f32 v[184:185], v[184:185], v[216:217]
	v_pk_add_f32 v[234:235], v[234:235], v[150:151]
	v_pk_add_f32 v[232:233], v[232:233], v[148:149]
	v_pk_add_f32 v[234:235], v[234:235], 1.0 op_sel_hi:[1,0]
	v_pk_add_f32 v[232:233], v[232:233], 1.0 op_sel_hi:[1,0]
	v_pk_mul_f32 v[202:203], v[202:203], v[234:235]
	v_pk_mul_f32 v[200:201], v[200:201], v[232:233]
	v_pk_add_f32 v[190:191], v[190:191], v[222:223]
	v_pk_add_f32 v[188:189], v[188:189], v[220:221]
	v_pk_add_f32 v[238:239], v[238:239], v[154:155]
	v_pk_add_f32 v[236:237], v[236:237], v[152:153]
	v_pk_add_f32 v[238:239], v[238:239], 1.0 op_sel_hi:[1,0]
	v_pk_add_f32 v[236:237], v[236:237], 1.0 op_sel_hi:[1,0]
	v_pk_mul_f32 v[206:207], v[206:207], v[238:239]
	v_pk_mul_f32 v[204:205], v[204:205], v[236:237]
	v_pk_add_f32 v[194:195], v[194:195], v[226:227]
	v_pk_add_f32 v[192:193], v[192:193], v[224:225]
	v_pk_add_f32 v[242:243], v[242:243], v[158:159]
	v_pk_add_f32 v[240:241], v[240:241], v[156:157]
	v_pk_add_f32 v[242:243], v[242:243], 1.0 op_sel_hi:[1,0]
	v_pk_add_f32 v[240:241], v[240:241], 1.0 op_sel_hi:[1,0]
	v_pk_mul_f32 v[210:211], v[210:211], v[242:243]
	v_pk_mul_f32 v[208:209], v[208:209], v[240:241]
	global_load_dwordx4 v[212:215], v179, s[18:19] nt
	global_load_dwordx4 v[216:219], v179, s[18:19] offset:16 nt
	global_load_dwordx4 v[220:223], v179, s[18:19] offset:512 nt
	global_load_dwordx4 v[224:227], v179, s[18:19] offset:528 nt
	s_add_u32 s18, s18, 0x10000
	s_addc_u32 s19, s19, 0
	global_load_dwordx4 v[228:231], v179, s[18:19] nt
	global_load_dwordx4 v[232:235], v179, s[18:19] offset:16 nt
	global_load_dwordx4 v[236:239], v179, s[18:19] offset:512 nt
	global_load_dwordx4 v[240:243], v179, s[18:19] offset:528 nt
	s_add_u32 s18, s18, 0x10000
	s_addc_u32 s19, s19, 0
	global_load_dwordx4 v[144:147], v179, s[18:19] nt
	global_load_dwordx4 v[148:151], v179, s[18:19] offset:16 nt
	global_load_dwordx4 v[152:155], v179, s[18:19] offset:512 nt
	global_load_dwordx4 v[156:159], v179, s[18:19] offset:528 nt
	s_add_u32 s18, s18, 0x50000
	s_addc_u32 s19, s19, 0
	s_mov_b32 s20, s14
	s_mov_b32 s21, s15
	s_mov_b32 s22, s94
	s_mov_b32 s23, s95
	s_waitcnt vmcnt(12)
	v_pk_fma_f32 v[126:127], v[126:127], v[182:183], v[162:163]
	v_pk_fma_f32 v[124:125], v[124:125], v[180:181], v[160:161]
	v_pk_fma_f32 v[122:123], v[122:123], v[186:187], v[166:167]
	v_pk_fma_f32 v[120:121], v[120:121], v[184:185], v[164:165]
	v_pk_fma_f32 v[118:119], v[118:119], v[190:191], v[170:171]
	v_pk_fma_f32 v[116:117], v[116:117], v[188:189], v[168:169]
	v_pk_fma_f32 v[114:115], v[114:115], v[194:195], v[246:247]
	v_pk_fma_f32 v[112:113], v[112:113], v[192:193], v[244:245]
	v_cvt_pk_bf16_f32 v248, v124, v125
	v_cvt_pk_bf16_f32 v249, v126, v127
	v_cvt_pk_bf16_f32 v250, v120, v121
	v_cvt_pk_bf16_f32 v251, v122, v123
	global_store_dwordx4 v252, v[248:251], s[20:21]
	v_mul_f32_e32 v160, v125, v125
	v_fmac_f32_e32 v160, v124, v124
	v_mul_f32_e32 v161, v127, v127
	v_fmac_f32_e32 v161, v126, v126
	v_add_f32_e32 v160, v160, v161
	v_mul_f32_e32 v161, v121, v121
	v_fmac_f32_e32 v161, v120, v120
	v_add_f32_e32 v160, v160, v161
	v_mul_f32_e32 v161, v123, v123
	v_fmac_f32_e32 v161, v122, v122
	v_add_f32_e32 v160, v161, v160
	v_pk_mul_f32 v[124:125], v[196:197], v[124:125]
	v_pk_mul_f32 v[126:127], v[198:199], v[126:127]
	v_pk_mul_f32 v[120:121], v[200:201], v[120:121]
	v_pk_mul_f32 v[122:123], v[202:203], v[122:123]
	v_cvt_pk_bf16_f32 v124, v124, v125
	v_cvt_pk_bf16_f32 v125, v126, v127
	v_cvt_pk_bf16_f32 v126, v120, v121
	v_cvt_pk_bf16_f32 v127, v122, v123
	global_store_dwordx4 v252, v[124:127], s[22:23]
	v_cvt_pk_bf16_f32 v248, v116, v117
	v_cvt_pk_bf16_f32 v249, v118, v119
	v_cvt_pk_bf16_f32 v250, v112, v113
	v_cvt_pk_bf16_f32 v251, v114, v115
	global_store_dwordx4 v252, v[248:251], s[20:21] offset:256
	v_mul_f32_e32 v162, v117, v117
	v_fmac_f32_e32 v162, v116, v116
	v_mul_f32_e32 v161, v119, v119
	v_fmac_f32_e32 v161, v118, v118
	v_add_f32_e32 v162, v162, v161
	v_mul_f32_e32 v161, v113, v113
	v_fmac_f32_e32 v161, v112, v112
	v_add_f32_e32 v162, v162, v161
	v_mul_f32_e32 v161, v115, v115
	v_fmac_f32_e32 v161, v114, v114
	v_add_f32_e32 v162, v161, v162
	v_pk_mul_f32 v[116:117], v[204:205], v[116:117]
	v_pk_mul_f32 v[118:119], v[206:207], v[118:119]
	v_pk_mul_f32 v[112:113], v[208:209], v[112:113]
	v_pk_mul_f32 v[114:115], v[210:211], v[114:115]
	v_cvt_pk_bf16_f32 v116, v116, v117
	v_cvt_pk_bf16_f32 v117, v118, v119
	v_cvt_pk_bf16_f32 v118, v112, v113
	v_cvt_pk_bf16_f32 v119, v114, v115
	global_store_dwordx4 v252, v[116:119], s[22:23] offset:256
	v_add_f32_e32 v160, v160, v162
	v_xor_b32_e32 v164, 16, v178
	v_lshlrev_b32_e32 v164, 2, v164
	ds_bpermute_b32 v165, v164, v160
	v_xor_b32_e32 v164, 32, v178
	v_lshlrev_b32_e32 v164, 2, v164
	s_waitcnt lgkmcnt(0)
	v_add_f32_e32 v160, v160, v165
	ds_bpermute_b32 v165, v164, v160
	s_waitcnt lgkmcnt(0)
	v_add_f32_e32 v160, v160, v165
	s_mov_b64 s[30:31], exec
	s_and_b64 exec, exec, s[4:5]
	global_atomic_add_f32 v253, v160, s[96:97]
	s_mov_b64 exec, s[30:31]
	global_load_dwordx4 v[160:163], v179, s[18:19] nt
	global_load_dwordx4 v[164:167], v179, s[18:19] offset:16 nt
	global_load_dwordx4 v[168:171], v179, s[18:19] offset:512 nt
	global_load_dwordx4 v[244:247], v179, s[18:19] offset:528 nt
	s_add_u32 s18, s18, 0x10000
	s_addc_u32 s19, s19, 0
	s_add_u32 s20, s20, 0x8000
	s_addc_u32 s21, s21, 0
	s_add_u32 s22, s22, 0x8000
	s_addc_u32 s23, s23, 0
	s_waitcnt vmcnt(16)
	v_pk_fma_f32 v[110:111], v[110:111], v[182:183], v[214:215]
	v_pk_fma_f32 v[108:109], v[108:109], v[180:181], v[212:213]
	v_pk_fma_f32 v[106:107], v[106:107], v[186:187], v[218:219]
	v_pk_fma_f32 v[104:105], v[104:105], v[184:185], v[216:217]
	v_pk_fma_f32 v[102:103], v[102:103], v[190:191], v[222:223]
	v_pk_fma_f32 v[100:101], v[100:101], v[188:189], v[220:221]
	v_pk_fma_f32 v[98:99], v[98:99], v[194:195], v[226:227]
	v_pk_fma_f32 v[96:97], v[96:97], v[192:193], v[224:225]
	v_cvt_pk_bf16_f32 v248, v108, v109
	v_cvt_pk_bf16_f32 v249, v110, v111
	v_cvt_pk_bf16_f32 v250, v104, v105
	v_cvt_pk_bf16_f32 v251, v106, v107
	global_store_dwordx4 v252, v[248:251], s[20:21]
	v_mul_f32_e32 v212, v109, v109
	v_fmac_f32_e32 v212, v108, v108
	v_mul_f32_e32 v213, v111, v111
	v_fmac_f32_e32 v213, v110, v110
	v_add_f32_e32 v212, v212, v213
	v_mul_f32_e32 v213, v105, v105
	v_fmac_f32_e32 v213, v104, v104
	v_add_f32_e32 v212, v212, v213
	v_mul_f32_e32 v213, v107, v107
	v_fmac_f32_e32 v213, v106, v106
	v_add_f32_e32 v212, v213, v212
	v_pk_mul_f32 v[108:109], v[196:197], v[108:109]
	v_pk_mul_f32 v[110:111], v[198:199], v[110:111]
	v_pk_mul_f32 v[104:105], v[200:201], v[104:105]
	v_pk_mul_f32 v[106:107], v[202:203], v[106:107]
	v_cvt_pk_bf16_f32 v108, v108, v109
	v_cvt_pk_bf16_f32 v109, v110, v111
	v_cvt_pk_bf16_f32 v110, v104, v105
	v_cvt_pk_bf16_f32 v111, v106, v107
	global_store_dwordx4 v252, v[108:111], s[22:23]
	v_cvt_pk_bf16_f32 v248, v100, v101
	v_cvt_pk_bf16_f32 v249, v102, v103
	v_cvt_pk_bf16_f32 v250, v96, v97
	v_cvt_pk_bf16_f32 v251, v98, v99
	global_store_dwordx4 v252, v[248:251], s[20:21] offset:256
	v_mul_f32_e32 v214, v101, v101
	v_fmac_f32_e32 v214, v100, v100
	v_mul_f32_e32 v213, v103, v103
	v_fmac_f32_e32 v213, v102, v102
	v_add_f32_e32 v214, v214, v213
	v_mul_f32_e32 v213, v97, v97
	v_fmac_f32_e32 v213, v96, v96
	v_add_f32_e32 v214, v214, v213
	v_mul_f32_e32 v213, v99, v99
	v_fmac_f32_e32 v213, v98, v98
	v_add_f32_e32 v214, v213, v214
	v_pk_mul_f32 v[100:101], v[204:205], v[100:101]
	v_pk_mul_f32 v[102:103], v[206:207], v[102:103]
	v_pk_mul_f32 v[96:97], v[208:209], v[96:97]
	v_pk_mul_f32 v[98:99], v[210:211], v[98:99]
	v_cvt_pk_bf16_f32 v100, v100, v101
	v_cvt_pk_bf16_f32 v101, v102, v103
	v_cvt_pk_bf16_f32 v102, v96, v97
	v_cvt_pk_bf16_f32 v103, v98, v99
	global_store_dwordx4 v252, v[100:103], s[22:23] offset:256
	v_add_f32_e32 v212, v212, v214
	v_xor_b32_e32 v216, 16, v178
	v_lshlrev_b32_e32 v216, 2, v216
	ds_bpermute_b32 v217, v216, v212
	v_xor_b32_e32 v216, 32, v178
	v_lshlrev_b32_e32 v216, 2, v216
	s_waitcnt lgkmcnt(0)
	v_add_f32_e32 v212, v212, v217
	ds_bpermute_b32 v217, v216, v212
	s_waitcnt lgkmcnt(0)
	v_add_f32_e32 v212, v212, v217
	s_mov_b64 s[30:31], exec
	s_and_b64 exec, exec, s[4:5]
	global_atomic_add_f32 v253, v212, s[96:97] offset:64
	s_mov_b64 exec, s[30:31]
	global_load_dwordx4 v[212:215], v179, s[18:19] nt
	global_load_dwordx4 v[216:219], v179, s[18:19] offset:16 nt
	global_load_dwordx4 v[220:223], v179, s[18:19] offset:512 nt
	global_load_dwordx4 v[224:227], v179, s[18:19] offset:528 nt
	s_add_u32 s18, s18, 0x10000
	s_addc_u32 s19, s19, 0
	s_add_u32 s20, s20, 0x8000
	s_addc_u32 s21, s21, 0
	s_add_u32 s22, s22, 0x8000
	s_addc_u32 s23, s23, 0
	s_waitcnt vmcnt(20)
	v_pk_fma_f32 v[94:95], v[94:95], v[182:183], v[230:231]
	v_pk_fma_f32 v[92:93], v[92:93], v[180:181], v[228:229]
	v_pk_fma_f32 v[90:91], v[90:91], v[186:187], v[234:235]
	v_pk_fma_f32 v[88:89], v[88:89], v[184:185], v[232:233]
	v_pk_fma_f32 v[86:87], v[86:87], v[190:191], v[238:239]
	v_pk_fma_f32 v[84:85], v[84:85], v[188:189], v[236:237]
	v_pk_fma_f32 v[82:83], v[82:83], v[194:195], v[242:243]
	v_pk_fma_f32 v[80:81], v[80:81], v[192:193], v[240:241]
	v_cvt_pk_bf16_f32 v248, v92, v93
	v_cvt_pk_bf16_f32 v249, v94, v95
	v_cvt_pk_bf16_f32 v250, v88, v89
	v_cvt_pk_bf16_f32 v251, v90, v91
	global_store_dwordx4 v252, v[248:251], s[20:21]
	v_mul_f32_e32 v228, v93, v93
	v_fmac_f32_e32 v228, v92, v92
	v_mul_f32_e32 v229, v95, v95
	v_fmac_f32_e32 v229, v94, v94
	v_add_f32_e32 v228, v228, v229
	v_mul_f32_e32 v229, v89, v89
	v_fmac_f32_e32 v229, v88, v88
	v_add_f32_e32 v228, v228, v229
	v_mul_f32_e32 v229, v91, v91
	v_fmac_f32_e32 v229, v90, v90
	v_add_f32_e32 v228, v229, v228
	v_pk_mul_f32 v[92:93], v[196:197], v[92:93]
	v_pk_mul_f32 v[94:95], v[198:199], v[94:95]
	v_pk_mul_f32 v[88:89], v[200:201], v[88:89]
	v_pk_mul_f32 v[90:91], v[202:203], v[90:91]
	v_cvt_pk_bf16_f32 v92, v92, v93
	v_cvt_pk_bf16_f32 v93, v94, v95
	v_cvt_pk_bf16_f32 v94, v88, v89
	v_cvt_pk_bf16_f32 v95, v90, v91
	global_store_dwordx4 v252, v[92:95], s[22:23]
	v_cvt_pk_bf16_f32 v248, v84, v85
	v_cvt_pk_bf16_f32 v249, v86, v87
	v_cvt_pk_bf16_f32 v250, v80, v81
	v_cvt_pk_bf16_f32 v251, v82, v83
	global_store_dwordx4 v252, v[248:251], s[20:21] offset:256
	v_mul_f32_e32 v230, v85, v85
	v_fmac_f32_e32 v230, v84, v84
	v_mul_f32_e32 v229, v87, v87
	v_fmac_f32_e32 v229, v86, v86
	v_add_f32_e32 v230, v230, v229
	v_mul_f32_e32 v229, v81, v81
	v_fmac_f32_e32 v229, v80, v80
	v_add_f32_e32 v230, v230, v229
	v_mul_f32_e32 v229, v83, v83
	v_fmac_f32_e32 v229, v82, v82
	v_add_f32_e32 v230, v229, v230
	v_pk_mul_f32 v[84:85], v[204:205], v[84:85]
	v_pk_mul_f32 v[86:87], v[206:207], v[86:87]
	v_pk_mul_f32 v[80:81], v[208:209], v[80:81]
	v_pk_mul_f32 v[82:83], v[210:211], v[82:83]
	v_cvt_pk_bf16_f32 v84, v84, v85
	v_cvt_pk_bf16_f32 v85, v86, v87
	v_cvt_pk_bf16_f32 v86, v80, v81
	v_cvt_pk_bf16_f32 v87, v82, v83
	global_store_dwordx4 v252, v[84:87], s[22:23] offset:256
	v_add_f32_e32 v228, v228, v230
	v_xor_b32_e32 v232, 16, v178
	v_lshlrev_b32_e32 v232, 2, v232
	ds_bpermute_b32 v233, v232, v228
	v_xor_b32_e32 v232, 32, v178
	v_lshlrev_b32_e32 v232, 2, v232
	s_waitcnt lgkmcnt(0)
	v_add_f32_e32 v228, v228, v233
	ds_bpermute_b32 v233, v232, v228
	s_waitcnt lgkmcnt(0)
	v_add_f32_e32 v228, v228, v233
	s_mov_b64 s[30:31], exec
	s_and_b64 exec, exec, s[4:5]
	global_atomic_add_f32 v253, v228, s[96:97] offset:128
	s_mov_b64 exec, s[30:31]
	global_load_dwordx4 v[228:231], v179, s[18:19] nt
	global_load_dwordx4 v[232:235], v179, s[18:19] offset:16 nt
	global_load_dwordx4 v[236:239], v179, s[18:19] offset:512 nt
	global_load_dwordx4 v[240:243], v179, s[18:19] offset:528 nt
	s_add_u32 s18, s18, 0x10000
	s_addc_u32 s19, s19, 0
	s_add_u32 s20, s20, 0x8000
	s_addc_u32 s21, s21, 0
	s_add_u32 s22, s22, 0x8000
	s_addc_u32 s23, s23, 0
	s_waitcnt vmcnt(24)
	v_pk_fma_f32 v[78:79], v[78:79], v[182:183], v[146:147]
	v_pk_fma_f32 v[76:77], v[76:77], v[180:181], v[144:145]
	v_pk_fma_f32 v[74:75], v[74:75], v[186:187], v[150:151]
	v_pk_fma_f32 v[72:73], v[72:73], v[184:185], v[148:149]
	v_pk_fma_f32 v[70:71], v[70:71], v[190:191], v[154:155]
	v_pk_fma_f32 v[68:69], v[68:69], v[188:189], v[152:153]
	v_pk_fma_f32 v[66:67], v[66:67], v[194:195], v[158:159]
	v_pk_fma_f32 v[64:65], v[64:65], v[192:193], v[156:157]
	v_cvt_pk_bf16_f32 v248, v76, v77
	v_cvt_pk_bf16_f32 v249, v78, v79
	v_cvt_pk_bf16_f32 v250, v72, v73
	v_cvt_pk_bf16_f32 v251, v74, v75
	global_store_dwordx4 v252, v[248:251], s[20:21]
	v_mul_f32_e32 v144, v77, v77
	v_fmac_f32_e32 v144, v76, v76
	v_mul_f32_e32 v145, v79, v79
	v_fmac_f32_e32 v145, v78, v78
	v_add_f32_e32 v144, v144, v145
	v_mul_f32_e32 v145, v73, v73
	v_fmac_f32_e32 v145, v72, v72
	v_add_f32_e32 v144, v144, v145
	v_mul_f32_e32 v145, v75, v75
	v_fmac_f32_e32 v145, v74, v74
	v_add_f32_e32 v144, v145, v144
	v_pk_mul_f32 v[76:77], v[196:197], v[76:77]
	v_pk_mul_f32 v[78:79], v[198:199], v[78:79]
	v_pk_mul_f32 v[72:73], v[200:201], v[72:73]
	v_pk_mul_f32 v[74:75], v[202:203], v[74:75]
	v_cvt_pk_bf16_f32 v76, v76, v77
	v_cvt_pk_bf16_f32 v77, v78, v79
	v_cvt_pk_bf16_f32 v78, v72, v73
	v_cvt_pk_bf16_f32 v79, v74, v75
	global_store_dwordx4 v252, v[76:79], s[22:23]
	v_cvt_pk_bf16_f32 v248, v68, v69
	v_cvt_pk_bf16_f32 v249, v70, v71
	v_cvt_pk_bf16_f32 v250, v64, v65
	v_cvt_pk_bf16_f32 v251, v66, v67
	global_store_dwordx4 v252, v[248:251], s[20:21] offset:256
	v_mul_f32_e32 v146, v69, v69
	v_fmac_f32_e32 v146, v68, v68
	v_mul_f32_e32 v145, v71, v71
	v_fmac_f32_e32 v145, v70, v70
	v_add_f32_e32 v146, v146, v145
	v_mul_f32_e32 v145, v65, v65
	v_fmac_f32_e32 v145, v64, v64
	v_add_f32_e32 v146, v146, v145
	v_mul_f32_e32 v145, v67, v67
	v_fmac_f32_e32 v145, v66, v66
	v_add_f32_e32 v146, v145, v146
	v_pk_mul_f32 v[68:69], v[204:205], v[68:69]
	v_pk_mul_f32 v[70:71], v[206:207], v[70:71]
	v_pk_mul_f32 v[64:65], v[208:209], v[64:65]
	v_pk_mul_f32 v[66:67], v[210:211], v[66:67]
	v_cvt_pk_bf16_f32 v68, v68, v69
	v_cvt_pk_bf16_f32 v69, v70, v71
	v_cvt_pk_bf16_f32 v70, v64, v65
	v_cvt_pk_bf16_f32 v71, v66, v67
	global_store_dwordx4 v252, v[68:71], s[22:23] offset:256
	v_add_f32_e32 v144, v144, v146
	v_xor_b32_e32 v148, 16, v178
	v_lshlrev_b32_e32 v148, 2, v148
	ds_bpermute_b32 v149, v148, v144
	v_xor_b32_e32 v148, 32, v178
	v_lshlrev_b32_e32 v148, 2, v148
	s_waitcnt lgkmcnt(0)
	v_add_f32_e32 v144, v144, v149
	ds_bpermute_b32 v149, v148, v144
	s_waitcnt lgkmcnt(0)
	v_add_f32_e32 v144, v144, v149
	s_mov_b64 s[30:31], exec
	s_and_b64 exec, exec, s[4:5]
	global_atomic_add_f32 v253, v144, s[96:97] offset:192
	s_mov_b64 exec, s[30:31]
	global_load_dwordx4 v[144:147], v179, s[18:19] nt
	global_load_dwordx4 v[148:151], v179, s[18:19] offset:16 nt
	global_load_dwordx4 v[152:155], v179, s[18:19] offset:512 nt
	global_load_dwordx4 v[156:159], v179, s[18:19] offset:528 nt
	s_add_u32 s20, s20, 0x28000
	s_addc_u32 s21, s21, 0
	s_add_u32 s22, s22, 0x28000
	s_addc_u32 s23, s23, 0
	s_waitcnt vmcnt(24)
	v_pk_fma_f32 v[62:63], v[62:63], v[182:183], v[162:163]
	v_pk_fma_f32 v[60:61], v[60:61], v[180:181], v[160:161]
	v_pk_fma_f32 v[58:59], v[58:59], v[186:187], v[166:167]
	v_pk_fma_f32 v[56:57], v[56:57], v[184:185], v[164:165]
	v_pk_fma_f32 v[54:55], v[54:55], v[190:191], v[170:171]
	v_pk_fma_f32 v[52:53], v[52:53], v[188:189], v[168:169]
	v_pk_fma_f32 v[50:51], v[50:51], v[194:195], v[246:247]
	v_pk_fma_f32 v[48:49], v[48:49], v[192:193], v[244:245]
	v_cvt_pk_bf16_f32 v248, v60, v61
	v_cvt_pk_bf16_f32 v249, v62, v63
	v_cvt_pk_bf16_f32 v250, v56, v57
	v_cvt_pk_bf16_f32 v251, v58, v59
	global_store_dwordx4 v252, v[248:251], s[20:21]
	v_mul_f32_e32 v160, v61, v61
	v_fmac_f32_e32 v160, v60, v60
	v_mul_f32_e32 v161, v63, v63
	v_fmac_f32_e32 v161, v62, v62
	v_add_f32_e32 v160, v160, v161
	v_mul_f32_e32 v161, v57, v57
	v_fmac_f32_e32 v161, v56, v56
	v_add_f32_e32 v160, v160, v161
	v_mul_f32_e32 v161, v59, v59
	v_fmac_f32_e32 v161, v58, v58
	v_add_f32_e32 v160, v161, v160
	v_pk_mul_f32 v[60:61], v[196:197], v[60:61]
	v_pk_mul_f32 v[62:63], v[198:199], v[62:63]
	v_pk_mul_f32 v[56:57], v[200:201], v[56:57]
	v_pk_mul_f32 v[58:59], v[202:203], v[58:59]
	v_cvt_pk_bf16_f32 v60, v60, v61
	v_cvt_pk_bf16_f32 v61, v62, v63
	v_cvt_pk_bf16_f32 v62, v56, v57
	v_cvt_pk_bf16_f32 v63, v58, v59
	global_store_dwordx4 v252, v[60:63], s[22:23]
	v_cvt_pk_bf16_f32 v248, v52, v53
	v_cvt_pk_bf16_f32 v249, v54, v55
	v_cvt_pk_bf16_f32 v250, v48, v49
	v_cvt_pk_bf16_f32 v251, v50, v51
	global_store_dwordx4 v252, v[248:251], s[20:21] offset:256
	v_mul_f32_e32 v162, v53, v53
	v_fmac_f32_e32 v162, v52, v52
	v_mul_f32_e32 v161, v55, v55
	v_fmac_f32_e32 v161, v54, v54
	v_add_f32_e32 v162, v162, v161
	v_mul_f32_e32 v161, v49, v49
	v_fmac_f32_e32 v161, v48, v48
	v_add_f32_e32 v162, v162, v161
	v_mul_f32_e32 v161, v51, v51
	v_fmac_f32_e32 v161, v50, v50
	v_add_f32_e32 v162, v161, v162
	v_pk_mul_f32 v[52:53], v[204:205], v[52:53]
	v_pk_mul_f32 v[54:55], v[206:207], v[54:55]
	v_pk_mul_f32 v[48:49], v[208:209], v[48:49]
	v_pk_mul_f32 v[50:51], v[210:211], v[50:51]
	v_cvt_pk_bf16_f32 v52, v52, v53
	v_cvt_pk_bf16_f32 v53, v54, v55
	v_cvt_pk_bf16_f32 v54, v48, v49
	v_cvt_pk_bf16_f32 v55, v50, v51
	global_store_dwordx4 v252, v[52:55], s[22:23] offset:256
	v_add_f32_e32 v160, v160, v162
	v_xor_b32_e32 v164, 16, v178
	v_lshlrev_b32_e32 v164, 2, v164
	ds_bpermute_b32 v165, v164, v160
	v_xor_b32_e32 v164, 32, v178
	v_lshlrev_b32_e32 v164, 2, v164
	s_waitcnt lgkmcnt(0)
	v_add_f32_e32 v160, v160, v165
	ds_bpermute_b32 v165, v164, v160
	s_waitcnt lgkmcnt(0)
	v_add_f32_e32 v160, v160, v165
	s_mov_b64 s[30:31], exec
	s_and_b64 exec, exec, s[4:5]
	global_atomic_add_f32 v253, v160, s[96:97] offset:512
	s_mov_b64 exec, s[30:31]
	s_add_u32 s20, s20, 0x8000
	s_addc_u32 s21, s21, 0
	s_add_u32 s22, s22, 0x8000
	s_addc_u32 s23, s23, 0
	s_waitcnt vmcnt(20)
	v_pk_fma_f32 v[46:47], v[46:47], v[182:183], v[214:215]
	v_pk_fma_f32 v[44:45], v[44:45], v[180:181], v[212:213]
	v_pk_fma_f32 v[42:43], v[42:43], v[186:187], v[218:219]
	v_pk_fma_f32 v[40:41], v[40:41], v[184:185], v[216:217]
	v_pk_fma_f32 v[38:39], v[38:39], v[190:191], v[222:223]
	v_pk_fma_f32 v[36:37], v[36:37], v[188:189], v[220:221]
	v_pk_fma_f32 v[34:35], v[34:35], v[194:195], v[226:227]
	v_pk_fma_f32 v[32:33], v[32:33], v[192:193], v[224:225]
	v_cvt_pk_bf16_f32 v248, v44, v45
	v_cvt_pk_bf16_f32 v249, v46, v47
	v_cvt_pk_bf16_f32 v250, v40, v41
	v_cvt_pk_bf16_f32 v251, v42, v43
	global_store_dwordx4 v252, v[248:251], s[20:21]
	v_mul_f32_e32 v212, v45, v45
	v_fmac_f32_e32 v212, v44, v44
	v_mul_f32_e32 v213, v47, v47
	v_fmac_f32_e32 v213, v46, v46
	v_add_f32_e32 v212, v212, v213
	v_mul_f32_e32 v213, v41, v41
	v_fmac_f32_e32 v213, v40, v40
	v_add_f32_e32 v212, v212, v213
	v_mul_f32_e32 v213, v43, v43
	v_fmac_f32_e32 v213, v42, v42
	v_add_f32_e32 v212, v213, v212
	v_pk_mul_f32 v[44:45], v[196:197], v[44:45]
	v_pk_mul_f32 v[46:47], v[198:199], v[46:47]
	v_pk_mul_f32 v[40:41], v[200:201], v[40:41]
	v_pk_mul_f32 v[42:43], v[202:203], v[42:43]
	v_cvt_pk_bf16_f32 v44, v44, v45
	v_cvt_pk_bf16_f32 v45, v46, v47
	v_cvt_pk_bf16_f32 v46, v40, v41
	v_cvt_pk_bf16_f32 v47, v42, v43
	global_store_dwordx4 v252, v[44:47], s[22:23]
	v_cvt_pk_bf16_f32 v248, v36, v37
	v_cvt_pk_bf16_f32 v249, v38, v39
	v_cvt_pk_bf16_f32 v250, v32, v33
	v_cvt_pk_bf16_f32 v251, v34, v35
	global_store_dwordx4 v252, v[248:251], s[20:21] offset:256
	v_mul_f32_e32 v214, v37, v37
	v_fmac_f32_e32 v214, v36, v36
	v_mul_f32_e32 v213, v39, v39
	v_fmac_f32_e32 v213, v38, v38
	v_add_f32_e32 v214, v214, v213
	v_mul_f32_e32 v213, v33, v33
	v_fmac_f32_e32 v213, v32, v32
	v_add_f32_e32 v214, v214, v213
	v_mul_f32_e32 v213, v35, v35
	v_fmac_f32_e32 v213, v34, v34
	v_add_f32_e32 v214, v213, v214
	v_pk_mul_f32 v[36:37], v[204:205], v[36:37]
	v_pk_mul_f32 v[38:39], v[206:207], v[38:39]
	v_pk_mul_f32 v[32:33], v[208:209], v[32:33]
	v_pk_mul_f32 v[34:35], v[210:211], v[34:35]
	v_cvt_pk_bf16_f32 v36, v36, v37
	v_cvt_pk_bf16_f32 v37, v38, v39
	v_cvt_pk_bf16_f32 v38, v32, v33
	v_cvt_pk_bf16_f32 v39, v34, v35
	global_store_dwordx4 v252, v[36:39], s[22:23] offset:256
	v_add_f32_e32 v212, v212, v214
	v_xor_b32_e32 v216, 16, v178
	v_lshlrev_b32_e32 v216, 2, v216
	ds_bpermute_b32 v217, v216, v212
	v_xor_b32_e32 v216, 32, v178
	v_lshlrev_b32_e32 v216, 2, v216
	s_waitcnt lgkmcnt(0)
	v_add_f32_e32 v212, v212, v217
	ds_bpermute_b32 v217, v216, v212
	s_waitcnt lgkmcnt(0)
	v_add_f32_e32 v212, v212, v217
	s_mov_b64 s[30:31], exec
	s_and_b64 exec, exec, s[4:5]
	global_atomic_add_f32 v253, v212, s[96:97] offset:576
	s_mov_b64 exec, s[30:31]
	s_add_u32 s20, s20, 0x8000
	s_addc_u32 s21, s21, 0
	s_add_u32 s22, s22, 0x8000
	s_addc_u32 s23, s23, 0
	s_waitcnt vmcnt(16)
	v_pk_fma_f32 v[30:31], v[30:31], v[182:183], v[230:231]
	v_pk_fma_f32 v[28:29], v[28:29], v[180:181], v[228:229]
	v_pk_fma_f32 v[26:27], v[26:27], v[186:187], v[234:235]
	v_pk_fma_f32 v[24:25], v[24:25], v[184:185], v[232:233]
	v_pk_fma_f32 v[22:23], v[22:23], v[190:191], v[238:239]
	v_pk_fma_f32 v[20:21], v[20:21], v[188:189], v[236:237]
	v_pk_fma_f32 v[18:19], v[18:19], v[194:195], v[242:243]
	v_pk_fma_f32 v[16:17], v[16:17], v[192:193], v[240:241]
	v_cvt_pk_bf16_f32 v248, v28, v29
	v_cvt_pk_bf16_f32 v249, v30, v31
	v_cvt_pk_bf16_f32 v250, v24, v25
	v_cvt_pk_bf16_f32 v251, v26, v27
	global_store_dwordx4 v252, v[248:251], s[20:21]
	v_mul_f32_e32 v228, v29, v29
	v_fmac_f32_e32 v228, v28, v28
	v_mul_f32_e32 v229, v31, v31
	v_fmac_f32_e32 v229, v30, v30
	v_add_f32_e32 v228, v228, v229
	v_mul_f32_e32 v229, v25, v25
	v_fmac_f32_e32 v229, v24, v24
	v_add_f32_e32 v228, v228, v229
	v_mul_f32_e32 v229, v27, v27
	v_fmac_f32_e32 v229, v26, v26
	v_add_f32_e32 v228, v229, v228
	v_pk_mul_f32 v[28:29], v[196:197], v[28:29]
	v_pk_mul_f32 v[30:31], v[198:199], v[30:31]
	v_pk_mul_f32 v[24:25], v[200:201], v[24:25]
	v_pk_mul_f32 v[26:27], v[202:203], v[26:27]
	v_cvt_pk_bf16_f32 v28, v28, v29
	v_cvt_pk_bf16_f32 v29, v30, v31
	v_cvt_pk_bf16_f32 v30, v24, v25
	v_cvt_pk_bf16_f32 v31, v26, v27
	global_store_dwordx4 v252, v[28:31], s[22:23]
	v_cvt_pk_bf16_f32 v248, v20, v21
	v_cvt_pk_bf16_f32 v249, v22, v23
	v_cvt_pk_bf16_f32 v250, v16, v17
	v_cvt_pk_bf16_f32 v251, v18, v19
	global_store_dwordx4 v252, v[248:251], s[20:21] offset:256
	v_mul_f32_e32 v230, v21, v21
	v_fmac_f32_e32 v230, v20, v20
	v_mul_f32_e32 v229, v23, v23
	v_fmac_f32_e32 v229, v22, v22
	v_add_f32_e32 v230, v230, v229
	v_mul_f32_e32 v229, v17, v17
	v_fmac_f32_e32 v229, v16, v16
	v_add_f32_e32 v230, v230, v229
	v_mul_f32_e32 v229, v19, v19
	v_fmac_f32_e32 v229, v18, v18
	v_add_f32_e32 v230, v229, v230
	v_pk_mul_f32 v[20:21], v[204:205], v[20:21]
	v_pk_mul_f32 v[22:23], v[206:207], v[22:23]
	v_pk_mul_f32 v[16:17], v[208:209], v[16:17]
	v_pk_mul_f32 v[18:19], v[210:211], v[18:19]
	v_cvt_pk_bf16_f32 v20, v20, v21
	v_cvt_pk_bf16_f32 v21, v22, v23
	v_cvt_pk_bf16_f32 v22, v16, v17
	v_cvt_pk_bf16_f32 v23, v18, v19
	global_store_dwordx4 v252, v[20:23], s[22:23] offset:256
	v_add_f32_e32 v228, v228, v230
	v_xor_b32_e32 v232, 16, v178
	v_lshlrev_b32_e32 v232, 2, v232
	ds_bpermute_b32 v233, v232, v228
	v_xor_b32_e32 v232, 32, v178
	v_lshlrev_b32_e32 v232, 2, v232
	s_waitcnt lgkmcnt(0)
	v_add_f32_e32 v228, v228, v233
	ds_bpermute_b32 v233, v232, v228
	s_waitcnt lgkmcnt(0)
	v_add_f32_e32 v228, v228, v233
	s_mov_b64 s[30:31], exec
	s_and_b64 exec, exec, s[4:5]
	global_atomic_add_f32 v253, v228, s[96:97] offset:640
	s_mov_b64 exec, s[30:31]
	s_add_u32 s20, s20, 0x8000
	s_addc_u32 s21, s21, 0
	s_add_u32 s22, s22, 0x8000
	s_addc_u32 s23, s23, 0
	s_waitcnt vmcnt(12)
	v_pk_fma_f32 v[14:15], v[14:15], v[182:183], v[146:147]
	v_pk_fma_f32 v[12:13], v[12:13], v[180:181], v[144:145]
	v_pk_fma_f32 v[10:11], v[10:11], v[186:187], v[150:151]
	v_pk_fma_f32 v[8:9], v[8:9], v[184:185], v[148:149]
	v_pk_fma_f32 v[6:7], v[6:7], v[190:191], v[154:155]
	v_pk_fma_f32 v[4:5], v[4:5], v[188:189], v[152:153]
	v_pk_fma_f32 v[2:3], v[2:3], v[194:195], v[158:159]
	v_pk_fma_f32 v[0:1], v[0:1], v[192:193], v[156:157]
	v_cvt_pk_bf16_f32 v248, v12, v13
	v_cvt_pk_bf16_f32 v249, v14, v15
	v_cvt_pk_bf16_f32 v250, v8, v9
	v_cvt_pk_bf16_f32 v251, v10, v11
	global_store_dwordx4 v252, v[248:251], s[20:21]
	v_mul_f32_e32 v144, v13, v13
	v_fmac_f32_e32 v144, v12, v12
	v_mul_f32_e32 v145, v15, v15
	v_fmac_f32_e32 v145, v14, v14
	v_add_f32_e32 v144, v144, v145
	v_mul_f32_e32 v145, v9, v9
	v_fmac_f32_e32 v145, v8, v8
	v_add_f32_e32 v144, v144, v145
	v_mul_f32_e32 v145, v11, v11
	v_fmac_f32_e32 v145, v10, v10
	v_add_f32_e32 v144, v145, v144
	v_pk_mul_f32 v[12:13], v[196:197], v[12:13]
	v_pk_mul_f32 v[14:15], v[198:199], v[14:15]
	v_pk_mul_f32 v[8:9], v[200:201], v[8:9]
	v_pk_mul_f32 v[10:11], v[202:203], v[10:11]
	v_cvt_pk_bf16_f32 v12, v12, v13
	v_cvt_pk_bf16_f32 v13, v14, v15
	v_cvt_pk_bf16_f32 v14, v8, v9
	v_cvt_pk_bf16_f32 v15, v10, v11
	global_store_dwordx4 v252, v[12:15], s[22:23]
	v_cvt_pk_bf16_f32 v248, v4, v5
	v_cvt_pk_bf16_f32 v249, v6, v7
	v_cvt_pk_bf16_f32 v250, v0, v1
	v_cvt_pk_bf16_f32 v251, v2, v3
	global_store_dwordx4 v252, v[248:251], s[20:21] offset:256
	v_mul_f32_e32 v146, v5, v5
	v_fmac_f32_e32 v146, v4, v4
	v_mul_f32_e32 v145, v7, v7
	v_fmac_f32_e32 v145, v6, v6
	v_add_f32_e32 v146, v146, v145
	v_mul_f32_e32 v145, v1, v1
	v_fmac_f32_e32 v145, v0, v0
	v_add_f32_e32 v146, v146, v145
	v_mul_f32_e32 v145, v3, v3
	v_fmac_f32_e32 v145, v2, v2
	v_add_f32_e32 v146, v145, v146
	v_pk_mul_f32 v[4:5], v[204:205], v[4:5]
	v_pk_mul_f32 v[6:7], v[206:207], v[6:7]
	v_pk_mul_f32 v[0:1], v[208:209], v[0:1]
	v_pk_mul_f32 v[2:3], v[210:211], v[2:3]
	v_cvt_pk_bf16_f32 v4, v4, v5
	v_cvt_pk_bf16_f32 v5, v6, v7
	v_cvt_pk_bf16_f32 v6, v0, v1
	v_cvt_pk_bf16_f32 v7, v2, v3
	global_store_dwordx4 v252, v[4:7], s[22:23] offset:256
	v_add_f32_e32 v144, v144, v146
	v_xor_b32_e32 v148, 16, v178
	v_lshlrev_b32_e32 v148, 2, v148
	ds_bpermute_b32 v149, v148, v144
	v_xor_b32_e32 v148, 32, v178
	v_lshlrev_b32_e32 v148, 2, v148
	s_waitcnt lgkmcnt(0)
	v_add_f32_e32 v144, v144, v149
	ds_bpermute_b32 v149, v148, v144
	s_waitcnt lgkmcnt(0)
	v_add_f32_e32 v144, v144, v149
	s_mov_b64 s[30:31], exec
	s_and_b64 exec, exec, s[4:5]
	global_atomic_add_f32 v253, v144, s[96:97] offset:704
	s_mov_b64 exec, s[30:31]
	s_andn2_b64 vcc, exec, s[6:7]
	s_mov_b64 s[6:7], -1
	s_cbranch_vccnz .LBB0_578
	s_andn2_b64 vcc, exec, s[0:1]
	s_cbranch_vccnz .LBB0_577
	s_barrier
	s_branch .LBB0_577
